# MLA softmax: scale/subtract with v_pk_fma_f32 and row sums with v_pk_add_f32 (32 fewer VALU per tile)
# baseline (speedup 1.0000x reference)
.LBB0_561:
	s_waitcnt lgkmcnt(0)
	s_barrier
	v_add_f32_e32 v212, 0, v150
	v_add_f32_e32 v212, v152, v212
	v_add_f32_e32 v212, v145, v212
	v_add_f32_e32 v212, v151, v212
	v_add_f32_e32 v212, v146, v212
	v_add_f32_e32 v212, v149, v212
	v_add_f32_e32 v212, v147, v212
	v_add_f32_e32 v212, v148, v212
	v_add_f32_e32 v212, v93, v212
	v_add_f32_e32 v212, v95, v212
	v_add_f32_e32 v212, v91, v212
	v_add_f32_e32 v212, v94, v212
	v_add_f32_e32 v212, v89, v212
	v_add_f32_e32 v212, v92, v212
	v_add_f32_e32 v212, v88, v212
	v_add_f32_e32 v212, v90, v212
	v_mov_b32_e32 v213, 0
	s_mov_b32 s96, 0x3dd53b94
	v_cvt_pk_bf16_f32 v144, v150, v152
	v_cvt_pk_bf16_f32 v145, v145, v151
	v_cvt_pk_bf16_f32 v146, v146, v149
	v_cvt_pk_bf16_f32 v147, v147, v148
	v_cvt_pk_bf16_f32 v148, v93, v95
	v_cvt_pk_bf16_f32 v149, v91, v94
	v_cvt_pk_bf16_f32 v150, v89, v92
	v_cvt_pk_bf16_f32 v151, v88, v90
	v_mov_b32_e32 v72, v70
	v_mov_b32_e32 v73, v71
	v_mov_b32_e32 v74, v68
	v_mov_b32_e32 v75, v69
	v_mov_b32_e32 v76, v66
	v_mov_b32_e32 v77, v67
	v_mov_b32_e32 v78, v64
	v_mov_b32_e32 v79, v65
	v_mov_b32_e32 v64, v86
	v_mov_b32_e32 v65, v87
	v_mov_b32_e32 v66, v84
	v_mov_b32_e32 v67, v85
	v_mov_b32_e32 v68, v82
	v_mov_b32_e32 v69, v83
	v_mov_b32_e32 v70, v80
	v_mov_b32_e32 v71, v81
	v_permlane32_swap_b32_e32 v144, v146
	v_permlane32_swap_b32_e32 v145, v147
	v_permlane32_swap_b32_e32 v148, v150
	v_permlane32_swap_b32_e32 v149, v151

.Lmla_skipv_o:
	s_cmp_lt_u32 s58, s18
	s_cselect_b32 s0, 0, s18
	s_cselect_b32 s1, s6, s13
	s_lshl_b32 s0, s0, 6
	s_sub_i32 s0, s1, s0
	s_add_i32 s0, s51, s0
	s_ashr_i32 s1, s0, 31
	s_lshl_b64 s[10:11], s[0:1], 12
	s_add_u32 s16, s20, s10
	s_addc_u32 s17, s21, s11
	s_mov_b32 m0, s23
	v_lshl_add_u64 v[254:255], v[160:161], 1, s[16:17]
	global_load_lds_dwordx4 v[254:255], off
	s_mov_b32 m0, s7
	v_lshl_add_u64 v[254:255], v[162:163], 1, s[16:17]
	global_load_lds_dwordx4 v[254:255], off
	s_mov_b32 m0, s30
	v_mad_i64_i32 v[254:255], s[0:1], s0, v180, v[168:169]
	global_load_lds_dwordx4 v[254:255], off
	s_add_u32 s100, s16, 0x100
	s_addc_u32 s101, s17, 0
	v_exp_f32_e32 v64, v64
	v_exp_f32_e32 v65, v65
	v_exp_f32_e32 v66, v66
	v_exp_f32_e32 v67, v67
	v_pk_add_f32 v[212:213], v[212:213], v[64:65]
	v_exp_f32_e32 v68, v68
	s_waitcnt lgkmcnt(3)
	v_mfma_f32_32x32x16_bf16 v[80:95], v[230:233], v[124:127], 0
	ds_read_b128 v[230:233], v189 offset:57344
	v_exp_f32_e32 v69, v69
	v_pk_add_f32 v[212:213], v[212:213], v[66:67]
	v_exp_f32_e32 v70, v70
	s_waitcnt lgkmcnt(3)
	v_mfma_f32_32x32x16_bf16 v[80:95], v[234:237], v[120:123], v[80:95]
	ds_read_b128 v[234:237], v190 offset:57344
	v_exp_f32_e32 v71, v71
	v_pk_add_f32 v[212:213], v[212:213], v[68:69]
	v_exp_f32_e32 v72, v72
	s_waitcnt lgkmcnt(3)
	v_mfma_f32_32x32x16_bf16 v[80:95], v[238:241], v[116:119], v[80:95]
	ds_read_b128 v[238:241], v191 offset:57344
	v_exp_f32_e32 v73, v73
	v_pk_add_f32 v[212:213], v[212:213], v[70:71]
	v_exp_f32_e32 v74, v74
	s_waitcnt lgkmcnt(3)
	v_mfma_f32_32x32x16_bf16 v[80:95], v[242:245], v[112:115], v[80:95]
	ds_read_b128 v[242:245], v192 offset:57344
	v_exp_f32_e32 v75, v75
	v_pk_add_f32 v[212:213], v[212:213], v[72:73]
	v_exp_f32_e32 v76, v76
	s_waitcnt lgkmcnt(3)
	v_mfma_f32_32x32x16_bf16 v[80:95], v[230:233], v[108:111], v[80:95]
	v_add_u32_e32 v211, 0x6000, v203
	ds_read_b128 v[230:233], v211 offset:49152
	v_exp_f32_e32 v77, v77
	v_pk_add_f32 v[212:213], v[212:213], v[74:75]
	v_exp_f32_e32 v78, v78
	s_waitcnt lgkmcnt(3)
	v_mfma_f32_32x32x16_bf16 v[80:95], v[234:237], v[104:107], v[80:95]
	v_add_u32_e32 v211, 0x6000, v204
	ds_read_b128 v[234:237], v211 offset:49152
	v_exp_f32_e32 v79, v79
	v_pk_add_f32 v[212:213], v[212:213], v[76:77]
	v_pk_add_f32 v[212:213], v[212:213], v[78:79]
	s_waitcnt lgkmcnt(3)
	v_mfma_f32_32x32x16_bf16 v[80:95], v[238:241], v[100:103], v[80:95]
	v_add_u32_e32 v211, 0x6000, v205
	ds_read_b128 v[238:241], v211 offset:49152
	v_add_f32_e32 v212, v212, v213
	v_mov_b32_e32 v213, v212
	v_cvt_pk_bf16_f32 v152, v64, v65
	s_waitcnt lgkmcnt(3)
	v_mfma_f32_32x32x16_bf16 v[80:95], v[242:245], v[96:99], v[80:95]
	v_add_u32_e32 v211, 0x6000, v206
	ds_read_b128 v[242:245], v211 offset:49152
	v_cvt_pk_bf16_f32 v153, v66, v67
	v_cvt_pk_bf16_f32 v154, v68, v69
	v_cvt_pk_bf16_f32 v155, v70, v71
	s_waitcnt lgkmcnt(3)
	v_mfma_f32_32x32x16_bf16 v[80:95], v[230:233], v[128:131], v[80:95]
	v_add_u32_e32 v211, v209, v194
	ds_read_b128 v[230:233], v211 offset:8192
	v_cvt_pk_bf16_f32 v156, v72, v73
	v_cvt_pk_bf16_f32 v157, v74, v75
	v_cvt_pk_bf16_f32 v158, v76, v77
	s_waitcnt lgkmcnt(3)
	v_mfma_f32_32x32x16_bf16 v[80:95], v[234:237], v[132:135], v[80:95]
	v_add_u32_e32 v211, v209, v195
	ds_read_b128 v[234:237], v211 offset:8192
	v_cvt_pk_bf16_f32 v159, v78, v79
	v_permlane32_swap_b32_e32 v212, v213
	v_add_f32_e32 v251, v212, v213
	s_waitcnt lgkmcnt(3)
	v_mfma_f32_32x32x16_bf16 v[80:95], v[238:241], v[136:139], v[80:95]
	v_add_u32_e32 v211, v209, v196
	ds_read_b128 v[238:241], v211 offset:8192
	v_fma_f32 v183, v207, v183, v251
	v_permlane32_swap_b32_e32 v152, v154
	v_permlane32_swap_b32_e32 v153, v155
	s_waitcnt lgkmcnt(3)
	v_mfma_f32_32x32x16_bf16 v[80:95], v[242:245], v[140:143], v[80:95]
	v_add_u32_e32 v211, v209, v197
	ds_read_b128 v[242:245], v211 offset:8192
	v_permlane32_swap_b32_e32 v156, v158
	v_permlane32_swap_b32_e32 v157, v159
	s_waitcnt lgkmcnt(3)
	v_mfma_f32_32x32x16_bf16 v[64:79], v[230:233], v[124:127], 0
	v_add_u32_e32 v211, v209, v198
	ds_read_b128 v[230:233], v211 offset:8192
	s_waitcnt lgkmcnt(3)
	v_mfma_f32_32x32x16_bf16 v[64:79], v[234:237], v[120:123], v[64:79]
	v_add_u32_e32 v211, v209, v199
	ds_read_b128 v[234:237], v211 offset:8192
	s_waitcnt lgkmcnt(3)
	v_mfma_f32_32x32x16_bf16 v[64:79], v[238:241], v[116:119], v[64:79]
	v_add_u32_e32 v211, v209, v200
	ds_read_b128 v[238:241], v211 offset:8192
	s_waitcnt lgkmcnt(3)
	v_mfma_f32_32x32x16_bf16 v[64:79], v[242:245], v[112:115], v[64:79]
	v_add_u32_e32 v211, v209, v201
	ds_read_b128 v[242:245], v211 offset:8192
	s_waitcnt lgkmcnt(3)
	v_mfma_f32_32x32x16_bf16 v[64:79], v[230:233], v[108:111], v[64:79]
	v_add_u32_e32 v211, 0x6000, v203
	ds_read_b128 v[230:233], v211 offset:53248
	s_waitcnt lgkmcnt(3)
	v_mfma_f32_32x32x16_bf16 v[64:79], v[234:237], v[104:107], v[64:79]
	v_add_u32_e32 v211, 0x6000, v204
	ds_read_b128 v[234:237], v211 offset:53248
	s_waitcnt lgkmcnt(3)
	v_mfma_f32_32x32x16_bf16 v[64:79], v[238:241], v[100:103], v[64:79]
	v_add_u32_e32 v211, 0x6000, v205
	ds_read_b128 v[238:241], v211 offset:53248
	v_max_f32_e32 v249, v80, v81
	v_max3_f32 v249, v249, v82, v83
	s_waitcnt lgkmcnt(3)
	v_mfma_f32_32x32x16_bf16 v[64:79], v[242:245], v[96:99], v[64:79]
	v_add_u32_e32 v211, 0x6000, v206
	ds_read_b128 v[242:245], v211 offset:53248
	v_max3_f32 v249, v249, v84, v85
	v_max3_f32 v249, v249, v86, v87
	s_waitcnt lgkmcnt(3)
	v_mfma_f32_32x32x16_bf16 v[64:79], v[230:233], v[128:131], v[64:79]
	ds_read_b64_tr_b16 v[214:215], v185
	ds_read_b64_tr_b16 v[216:217], v185 offset:2048
	v_max3_f32 v249, v249, v88, v89
	v_max3_f32 v249, v249, v90, v91
	s_waitcnt lgkmcnt(4)
	v_mfma_f32_32x32x16_bf16 v[64:79], v[234:237], v[132:135], v[64:79]
	ds_read_b64_tr_b16 v[218:219], v185 offset:4096
	ds_read_b64_tr_b16 v[220:221], v185 offset:6144
	v_max3_f32 v249, v249, v92, v93
	v_max3_f32 v249, v249, v94, v95
	s_waitcnt lgkmcnt(5)
	v_mfma_f32_32x32x16_bf16 v[64:79], v[238:241], v[136:139], v[64:79]
	ds_read_b64_tr_b16 v[222:223], v185 offset:8192
	ds_read_b64_tr_b16 v[224:225], v185 offset:10240
	s_waitcnt lgkmcnt(6)
	v_mfma_f32_32x32x16_bf16 v[64:79], v[242:245], v[140:143], v[64:79]
	ds_read_b64_tr_b16 v[226:227], v185 offset:12288
	ds_read_b64_tr_b16 v[228:229], v185 offset:14336
	s_waitcnt lgkmcnt(6)
	v_mfma_f32_32x32x16_bf16 v[0:15], v[144:147], v[214:217], v[0:15]
	ds_read_b64_tr_b16 v[214:215], v185 offset:512
	ds_read_b64_tr_b16 v[216:217], v185 offset:2560
	s_waitcnt lgkmcnt(6)
	v_mfma_f32_32x32x16_bf16 v[0:15], v[148:151], v[218:221], v[0:15]
	ds_read_b64_tr_b16 v[218:219], v185 offset:4608
	ds_read_b64_tr_b16 v[220:221], v185 offset:6656
	s_waitcnt lgkmcnt(6)
	v_mfma_f32_32x32x16_bf16 v[0:15], v[152:155], v[222:225], v[0:15]
	ds_read_b64_tr_b16 v[222:223], v185 offset:8704
	ds_read_b64_tr_b16 v[224:225], v185 offset:10752
	s_waitcnt lgkmcnt(6)
	v_mfma_f32_32x32x16_bf16 v[0:15], v[156:159], v[226:229], v[0:15]
	ds_read_b64_tr_b16 v[226:227], v185 offset:12800
	ds_read_b64_tr_b16 v[228:229], v185 offset:14848
	s_waitcnt lgkmcnt(6)
	v_mfma_f32_32x32x16_bf16 v[48:63], v[144:147], v[214:217], v[48:63]
	ds_read_b64_tr_b16 v[214:215], v185 offset:1024
	ds_read_b64_tr_b16 v[216:217], v185 offset:3072
	v_max3_f32 v249, v249, v64, v65
	v_max3_f32 v249, v249, v66, v67
	v_max3_f32 v249, v249, v68, v69
	v_max3_f32 v249, v249, v70, v71
	v_max3_f32 v249, v249, v72, v73
	v_max3_f32 v249, v249, v74, v75
	s_waitcnt lgkmcnt(6)
	v_mfma_f32_32x32x16_bf16 v[48:63], v[148:151], v[218:221], v[48:63]
	ds_read_b64_tr_b16 v[218:219], v185 offset:5120
	ds_read_b64_tr_b16 v[220:221], v185 offset:7168
	v_max3_f32 v249, v249, v76, v77
	v_max3_f32 v249, v249, v78, v79
	v_mov_b32_e32 v250, v249
	s_nop 1
	v_permlane32_swap_b32_e32 v249, v250
	v_max_f32_e32 v249, v249, v250
	s_waitcnt lgkmcnt(6)
	v_mfma_f32_32x32x16_bf16 v[48:63], v[152:155], v[222:225], v[48:63]
	ds_read_b64_tr_b16 v[222:223], v185 offset:9216
	ds_read_b64_tr_b16 v[224:225], v185 offset:11264
	v_sub_f32_e32 v250, v249, v208
	v_cmp_ge_f32_e32 vcc, s40, v250
	v_max_f32_e32 v249, v208, v249
	v_sub_f32_e32 v250, v208, v249
	v_mul_f32_e32 v250, 0x3dd53b94, v250
	s_waitcnt lgkmcnt(6)
	v_mfma_f32_32x32x16_bf16 v[48:63], v[156:159], v[226:229], v[48:63]
	ds_read_b64_tr_b16 v[226:227], v185 offset:13312
	ds_read_b64_tr_b16 v[228:229], v185 offset:15360
	v_exp_f32_e32 v250, v250
	s_cmp_eq_u64 vcc, exec
	s_cselect_b64 s[10:11], -1, 0
	v_cndmask_b32_e64 v207, v250, 1.0, s[10:11]
	v_cndmask_b32_e64 v208, v249, v208, s[10:11]
	s_waitcnt lgkmcnt(6)
	v_mfma_f32_32x32x16_bf16 v[32:47], v[144:147], v[214:217], v[32:47]
	ds_read_b64_tr_b16 v[214:215], v185 offset:1536
	ds_read_b64_tr_b16 v[216:217], v185 offset:3584
	v_mul_f32_e32 v252, 0xbdd53b94, v208
	v_pk_fma_f32 v[80:81], v[80:81], s[96:97], v[252:253] op_sel_hi:[1,0,0]
	v_pk_fma_f32 v[82:83], v[82:83], s[96:97], v[252:253] op_sel_hi:[1,0,0]
	v_pk_fma_f32 v[84:85], v[84:85], s[96:97], v[252:253] op_sel_hi:[1,0,0]
	v_pk_fma_f32 v[86:87], v[86:87], s[96:97], v[252:253] op_sel_hi:[1,0,0]
	s_waitcnt lgkmcnt(6)
	v_mfma_f32_32x32x16_bf16 v[32:47], v[148:151], v[218:221], v[32:47]
	ds_read_b64_tr_b16 v[218:219], v185 offset:5632
	ds_read_b64_tr_b16 v[220:221], v185 offset:7680
	v_pk_fma_f32 v[88:89], v[88:89], s[96:97], v[252:253] op_sel_hi:[1,0,0]
	v_pk_fma_f32 v[90:91], v[90:91], s[96:97], v[252:253] op_sel_hi:[1,0,0]
	v_pk_fma_f32 v[92:93], v[92:93], s[96:97], v[252:253] op_sel_hi:[1,0,0]
	v_pk_fma_f32 v[94:95], v[94:95], s[96:97], v[252:253] op_sel_hi:[1,0,0]
	v_exp_f32_e32 v80, v80
	s_waitcnt lgkmcnt(6)
	v_mfma_f32_32x32x16_bf16 v[32:47], v[152:155], v[222:225], v[32:47]
	ds_read_b64_tr_b16 v[222:223], v185 offset:9728
	ds_read_b64_tr_b16 v[224:225], v185 offset:11776
	v_pk_fma_f32 v[64:65], v[64:65], s[96:97], v[252:253] op_sel_hi:[1,0,0]
	v_exp_f32_e32 v81, v81
	v_exp_f32_e32 v82, v82
	v_pk_fma_f32 v[66:67], v[66:67], s[96:97], v[252:253] op_sel_hi:[1,0,0]
	v_exp_f32_e32 v83, v83
	s_waitcnt lgkmcnt(6)
	v_mfma_f32_32x32x16_bf16 v[32:47], v[156:159], v[226:229], v[32:47]
	ds_read_b64_tr_b16 v[226:227], v185 offset:13824
	ds_read_b64_tr_b16 v[228:229], v185 offset:15872
	v_exp_f32_e32 v84, v84
	v_pk_fma_f32 v[68:69], v[68:69], s[96:97], v[252:253] op_sel_hi:[1,0,0]
	v_exp_f32_e32 v85, v85
	v_pk_add_f32 v[212:213], v[80:81], v[82:83]
	v_exp_f32_e32 v86, v86
	s_waitcnt lgkmcnt(6)
	v_mfma_f32_32x32x16_bf16 v[16:31], v[144:147], v[214:217], v[16:31]
	v_pk_fma_f32 v[70:71], v[70:71], s[96:97], v[252:253] op_sel_hi:[1,0,0]
	v_exp_f32_e32 v87, v87
	v_pk_add_f32 v[212:213], v[212:213], v[84:85]
	v_exp_f32_e32 v88, v88
	v_pk_fma_f32 v[72:73], v[72:73], s[96:97], v[252:253] op_sel_hi:[1,0,0]
	s_waitcnt lgkmcnt(4)
	v_mfma_f32_32x32x16_bf16 v[16:31], v[148:151], v[218:221], v[16:31]
	v_exp_f32_e32 v89, v89
	v_pk_add_f32 v[212:213], v[212:213], v[86:87]
	v_exp_f32_e32 v90, v90
	v_pk_fma_f32 v[74:75], v[74:75], s[96:97], v[252:253] op_sel_hi:[1,0,0]
	v_exp_f32_e32 v91, v91
	s_waitcnt lgkmcnt(2)
	v_mfma_f32_32x32x16_bf16 v[16:31], v[152:155], v[222:225], v[16:31]
	v_pk_add_f32 v[212:213], v[212:213], v[88:89]
	v_exp_f32_e32 v92, v92
	v_pk_fma_f32 v[76:77], v[76:77], s[96:97], v[252:253] op_sel_hi:[1,0,0]
	v_exp_f32_e32 v93, v93
	v_pk_add_f32 v[212:213], v[212:213], v[90:91]
	s_waitcnt lgkmcnt(0)
	v_mfma_f32_32x32x16_bf16 v[16:31], v[156:159], v[226:229], v[16:31]
	v_exp_f32_e32 v94, v94
	v_pk_fma_f32 v[78:79], v[78:79], s[96:97], v[252:253] op_sel_hi:[1,0,0]
	v_exp_f32_e32 v95, v95
	v_pk_add_f32 v[212:213], v[212:213], v[92:93]
	v_pk_add_f32 v[212:213], v[212:213], v[94:95]
	v_cvt_pk_bf16_f32 v144, v80, v81
	v_cvt_pk_bf16_f32 v145, v82, v83
	v_cvt_pk_bf16_f32 v146, v84, v85
	v_cvt_pk_bf16_f32 v147, v86, v87
	v_cvt_pk_bf16_f32 v148, v88, v89
	v_cvt_pk_bf16_f32 v149, v90, v91
	v_cvt_pk_bf16_f32 v150, v92, v93
	v_cvt_pk_bf16_f32 v151, v94, v95
	v_permlane32_swap_b32_e32 v144, v146
	v_permlane32_swap_b32_e32 v145, v147
	v_permlane32_swap_b32_e32 v148, v150
	v_permlane32_swap_b32_e32 v149, v151
	v_cmp_gt_f32_e32 vcc, 1.0, v207
	s_cbranch_vccz .Lmla_noresc_o
	s_and_saveexec_b64 s[0:1], s[8:9]
	ds_write_b32 v182, v207 offset:128
	s_or_b64 exec, exec, s[0:1]
	s_waitcnt lgkmcnt(0)
	v_add_u32_e32 v253, s50, v181
	ds_read_b128 v[92:95], v253 offset:224
	ds_read_b128 v[88:91], v253 offset:192
	ds_read_b128 v[84:87], v253 offset:160
	ds_read_b128 v[80:83], v253 offset:128
	s_waitcnt lgkmcnt(3)
	v_pk_mul_f32 v[12:13], v[12:13], v[92:93]
	v_pk_mul_f32 v[14:15], v[14:15], v[94:95]
	v_pk_mul_f32 v[60:61], v[60:61], v[92:93]
	v_pk_mul_f32 v[62:63], v[62:63], v[94:95]
	v_pk_mul_f32 v[44:45], v[44:45], v[92:93]
	v_pk_mul_f32 v[46:47], v[46:47], v[94:95]
	v_pk_mul_f32 v[28:29], v[28:29], v[92:93]
	v_pk_mul_f32 v[30:31], v[30:31], v[94:95]
	s_waitcnt lgkmcnt(2)
	v_pk_mul_f32 v[8:9], v[8:9], v[88:89]
	v_pk_mul_f32 v[10:11], v[10:11], v[90:91]
	v_pk_mul_f32 v[56:57], v[56:57], v[88:89]
	v_pk_mul_f32 v[58:59], v[58:59], v[90:91]
	v_pk_mul_f32 v[40:41], v[40:41], v[88:89]
	v_pk_mul_f32 v[42:43], v[42:43], v[90:91]
	v_pk_mul_f32 v[24:25], v[24:25], v[88:89]
	v_pk_mul_f32 v[26:27], v[26:27], v[90:91]
	s_waitcnt lgkmcnt(1)
	v_pk_mul_f32 v[4:5], v[4:5], v[84:85]
	v_pk_mul_f32 v[6:7], v[6:7], v[86:87]
	v_pk_mul_f32 v[52:53], v[52:53], v[84:85]
	v_pk_mul_f32 v[54:55], v[54:55], v[86:87]
	v_pk_mul_f32 v[36:37], v[36:37], v[84:85]
	v_pk_mul_f32 v[38:39], v[38:39], v[86:87]
	v_pk_mul_f32 v[20:21], v[20:21], v[84:85]
	v_pk_mul_f32 v[22:23], v[22:23], v[86:87]
	s_waitcnt lgkmcnt(0)
	v_pk_mul_f32 v[0:1], v[0:1], v[80:81]
	v_pk_mul_f32 v[2:3], v[2:3], v[82:83]
	v_pk_mul_f32 v[48:49], v[48:49], v[80:81]
	v_pk_mul_f32 v[50:51], v[50:51], v[82:83]
	v_pk_mul_f32 v[32:33], v[32:33], v[80:81]
	v_pk_mul_f32 v[34:35], v[34:35], v[82:83]
	v_pk_mul_f32 v[16:17], v[16:17], v[80:81]
	v_pk_mul_f32 v[18:19], v[18:19], v[82:83]
.Lmla_noresc_o:
	s_add_i32 s58, s58, 1
	s_waitcnt vmcnt(0) lgkmcnt(0)
	s_barrier
	ds_read_b128 v[230:233], v193 offset:32768
	ds_read_b128 v[234:237], v186 offset:32768
	ds_read_b128 v[238:241], v187 offset:32768
	ds_read_b128 v[242:245], v188 offset:32768
	s_mov_b32 m0, s22
	v_lshl_add_u64 v[254:255], v[164:165], 1, s[100:101]
	global_load_lds_dwordx4 v[254:255], off
	s_mov_b32 m0, s31
	v_lshl_add_u64 v[254:255], v[166:167], 1, s[100:101]
	global_load_lds_dwordx4 v[254:255], off
	s_cmp_lt_u32 s58, s18
	s_cselect_b32 s0, 0, s18
	s_cselect_b32 s1, s6, s13
	s_lshl_b32 s0, s0, 6
	s_sub_i32 s0, s1, s0
	s_add_i32 s0, s51, s0
	s_add_i32 s0, s0, 64
	s_ashr_i32 s1, s0, 31
	s_lshl_b64 s[10:11], s[0:1], 12
	s_add_u32 s16, s20, s10
	s_addc_u32 s17, s21, s11
	s_mov_b32 m0, s44
	v_lshl_add_u64 v[254:255], v[160:161], 1, s[16:17]
	global_load_lds_dwordx4 v[254:255], off
	s_mov_b32 m0, s45
	v_lshl_add_u64 v[254:255], v[162:163], 1, s[16:17]
	global_load_lds_dwordx4 v[254:255], off
	s_mov_b32 m0, s49
	v_mad_i64_i32 v[254:255], s[0:1], s0, v180, v[168:169]
	global_load_lds_dwordx4 v[254:255], off
	s_add_u32 s100, s16, 0x100
	s_addc_u32 s101, s17, 0
	v_exp_f32_e32 v64, v64
	v_exp_f32_e32 v65, v65
	v_exp_f32_e32 v66, v66
	v_exp_f32_e32 v67, v67
	v_pk_add_f32 v[212:213], v[212:213], v[64:65]
	v_exp_f32_e32 v68, v68
	s_waitcnt lgkmcnt(3)
	v_mfma_f32_32x32x16_bf16 v[80:95], v[230:233], v[124:127], 0
	ds_read_b128 v[230:233], v189 offset:32768
	v_exp_f32_e32 v69, v69
	v_pk_add_f32 v[212:213], v[212:213], v[66:67]
	v_exp_f32_e32 v70, v70
	s_waitcnt lgkmcnt(3)
	v_mfma_f32_32x32x16_bf16 v[80:95], v[234:237], v[120:123], v[80:95]
	ds_read_b128 v[234:237], v190 offset:32768
	v_exp_f32_e32 v71, v71
	v_pk_add_f32 v[212:213], v[212:213], v[68:69]
	v_exp_f32_e32 v72, v72
	s_waitcnt lgkmcnt(3)
	v_mfma_f32_32x32x16_bf16 v[80:95], v[238:241], v[116:119], v[80:95]
	ds_read_b128 v[238:241], v191 offset:32768
	v_exp_f32_e32 v73, v73
	v_pk_add_f32 v[212:213], v[212:213], v[70:71]
	v_exp_f32_e32 v74, v74
	s_waitcnt lgkmcnt(3)
	v_mfma_f32_32x32x16_bf16 v[80:95], v[242:245], v[112:115], v[80:95]
	ds_read_b128 v[242:245], v192 offset:32768
	v_exp_f32_e32 v75, v75
	v_pk_add_f32 v[212:213], v[212:213], v[72:73]
	v_exp_f32_e32 v76, v76
	s_waitcnt lgkmcnt(3)
	v_mfma_f32_32x32x16_bf16 v[80:95], v[230:233], v[108:111], v[80:95]
	ds_read_b128 v[230:233], v203 offset:49152
	v_exp_f32_e32 v77, v77
	v_pk_add_f32 v[212:213], v[212:213], v[74:75]
	v_exp_f32_e32 v78, v78
	s_waitcnt lgkmcnt(3)
	v_mfma_f32_32x32x16_bf16 v[80:95], v[234:237], v[104:107], v[80:95]
	ds_read_b128 v[234:237], v204 offset:49152
	v_exp_f32_e32 v79, v79
	v_pk_add_f32 v[212:213], v[212:213], v[76:77]
	v_pk_add_f32 v[212:213], v[212:213], v[78:79]
	s_waitcnt lgkmcnt(3)
	v_mfma_f32_32x32x16_bf16 v[80:95], v[238:241], v[100:103], v[80:95]
	ds_read_b128 v[238:241], v205 offset:49152
	v_add_f32_e32 v212, v212, v213
	v_mov_b32_e32 v213, v212
	v_cvt_pk_bf16_f32 v152, v64, v65
	s_waitcnt lgkmcnt(3)
	v_mfma_f32_32x32x16_bf16 v[80:95], v[242:245], v[96:99], v[80:95]
	ds_read_b128 v[242:245], v206 offset:49152
	v_cvt_pk_bf16_f32 v153, v66, v67
	v_cvt_pk_bf16_f32 v154, v68, v69
	v_cvt_pk_bf16_f32 v155, v70, v71
	s_waitcnt lgkmcnt(3)
	v_mfma_f32_32x32x16_bf16 v[80:95], v[230:233], v[128:131], v[80:95]
	ds_read_b128 v[230:233], v193 offset:40960
	v_cvt_pk_bf16_f32 v156, v72, v73
	v_cvt_pk_bf16_f32 v157, v74, v75
	v_cvt_pk_bf16_f32 v158, v76, v77
	s_waitcnt lgkmcnt(3)
	v_mfma_f32_32x32x16_bf16 v[80:95], v[234:237], v[132:135], v[80:95]
	ds_read_b128 v[234:237], v186 offset:40960
	v_cvt_pk_bf16_f32 v159, v78, v79
	v_permlane32_swap_b32_e32 v212, v213
	v_add_f32_e32 v251, v212, v213
	s_waitcnt lgkmcnt(3)
	v_mfma_f32_32x32x16_bf16 v[80:95], v[238:241], v[136:139], v[80:95]
	ds_read_b128 v[238:241], v187 offset:40960
	v_fma_f32 v183, v207, v183, v251
	v_permlane32_swap_b32_e32 v152, v154
	v_permlane32_swap_b32_e32 v153, v155
	s_waitcnt lgkmcnt(3)
	v_mfma_f32_32x32x16_bf16 v[80:95], v[242:245], v[140:143], v[80:95]
	ds_read_b128 v[242:245], v188 offset:40960
	v_permlane32_swap_b32_e32 v156, v158
	v_permlane32_swap_b32_e32 v157, v159
	s_waitcnt lgkmcnt(3)
	v_mfma_f32_32x32x16_bf16 v[64:79], v[230:233], v[124:127], 0
	ds_read_b128 v[230:233], v189 offset:40960
	s_waitcnt lgkmcnt(3)
	v_mfma_f32_32x32x16_bf16 v[64:79], v[234:237], v[120:123], v[64:79]
	ds_read_b128 v[234:237], v190 offset:40960
	s_waitcnt lgkmcnt(3)
	v_mfma_f32_32x32x16_bf16 v[64:79], v[238:241], v[116:119], v[64:79]
	ds_read_b128 v[238:241], v191 offset:40960
	s_waitcnt lgkmcnt(3)
	v_mfma_f32_32x32x16_bf16 v[64:79], v[242:245], v[112:115], v[64:79]
	ds_read_b128 v[242:245], v192 offset:40960
	s_waitcnt lgkmcnt(3)
	v_mfma_f32_32x32x16_bf16 v[64:79], v[230:233], v[108:111], v[64:79]
	ds_read_b128 v[230:233], v203 offset:53248
	s_waitcnt lgkmcnt(3)
	v_mfma_f32_32x32x16_bf16 v[64:79], v[234:237], v[104:107], v[64:79]
	ds_read_b128 v[234:237], v204 offset:53248
	s_waitcnt lgkmcnt(3)
	v_mfma_f32_32x32x16_bf16 v[64:79], v[238:241], v[100:103], v[64:79]
	ds_read_b128 v[238:241], v205 offset:53248
	v_max_f32_e32 v249, v80, v81
	v_max3_f32 v249, v249, v82, v83
	s_waitcnt lgkmcnt(3)
	v_mfma_f32_32x32x16_bf16 v[64:79], v[242:245], v[96:99], v[64:79]
	ds_read_b128 v[242:245], v206 offset:53248
	v_max3_f32 v249, v249, v84, v85
	v_max3_f32 v249, v249, v86, v87
	s_waitcnt lgkmcnt(3)
	v_mfma_f32_32x32x16_bf16 v[64:79], v[230:233], v[128:131], v[64:79]
	ds_read_b64_tr_b16 v[214:215], v184
	ds_read_b64_tr_b16 v[216:217], v184 offset:2048
	v_max3_f32 v249, v249, v88, v89
	v_max3_f32 v249, v249, v90, v91
	s_waitcnt lgkmcnt(4)
	v_mfma_f32_32x32x16_bf16 v[64:79], v[234:237], v[132:135], v[64:79]
	ds_read_b64_tr_b16 v[218:219], v184 offset:4096
	ds_read_b64_tr_b16 v[220:221], v184 offset:6144
	v_max3_f32 v249, v249, v92, v93
	v_max3_f32 v249, v249, v94, v95
	s_waitcnt lgkmcnt(5)
	v_mfma_f32_32x32x16_bf16 v[64:79], v[238:241], v[136:139], v[64:79]
	ds_read_b64_tr_b16 v[222:223], v184 offset:8192
	ds_read_b64_tr_b16 v[224:225], v184 offset:10240
	s_waitcnt lgkmcnt(6)
	v_mfma_f32_32x32x16_bf16 v[64:79], v[242:245], v[140:143], v[64:79]
	ds_read_b64_tr_b16 v[226:227], v184 offset:12288
	ds_read_b64_tr_b16 v[228:229], v184 offset:14336
	s_waitcnt lgkmcnt(6)
	v_mfma_f32_32x32x16_bf16 v[0:15], v[144:147], v[214:217], v[0:15]
	ds_read_b64_tr_b16 v[214:215], v184 offset:512
	ds_read_b64_tr_b16 v[216:217], v184 offset:2560
	s_waitcnt lgkmcnt(6)
	v_mfma_f32_32x32x16_bf16 v[0:15], v[148:151], v[218:221], v[0:15]
	ds_read_b64_tr_b16 v[218:219], v184 offset:4608
	ds_read_b64_tr_b16 v[220:221], v184 offset:6656
	s_waitcnt lgkmcnt(6)
	v_mfma_f32_32x32x16_bf16 v[0:15], v[152:155], v[222:225], v[0:15]
	ds_read_b64_tr_b16 v[222:223], v184 offset:8704
	ds_read_b64_tr_b16 v[224:225], v184 offset:10752
	s_waitcnt lgkmcnt(6)
	v_mfma_f32_32x32x16_bf16 v[0:15], v[156:159], v[226:229], v[0:15]
	ds_read_b64_tr_b16 v[226:227], v184 offset:12800
	ds_read_b64_tr_b16 v[228:229], v184 offset:14848
	s_waitcnt lgkmcnt(6)
	v_mfma_f32_32x32x16_bf16 v[48:63], v[144:147], v[214:217], v[48:63]
	ds_read_b64_tr_b16 v[214:215], v184 offset:1024
	ds_read_b64_tr_b16 v[216:217], v184 offset:3072
	v_max3_f32 v249, v249, v64, v65
	v_max3_f32 v249, v249, v66, v67
	v_max3_f32 v249, v249, v68, v69
	v_max3_f32 v249, v249, v70, v71
	v_max3_f32 v249, v249, v72, v73
	v_max3_f32 v249, v249, v74, v75
	s_waitcnt lgkmcnt(6)
	v_mfma_f32_32x32x16_bf16 v[48:63], v[148:151], v[218:221], v[48:63]
	ds_read_b64_tr_b16 v[218:219], v184 offset:5120
	ds_read_b64_tr_b16 v[220:221], v184 offset:7168
	v_max3_f32 v249, v249, v76, v77
	v_max3_f32 v249, v249, v78, v79
	v_mov_b32_e32 v250, v249
	s_nop 1
	v_permlane32_swap_b32_e32 v249, v250
	v_max_f32_e32 v249, v249, v250
	s_waitcnt lgkmcnt(6)
	v_mfma_f32_32x32x16_bf16 v[48:63], v[152:155], v[222:225], v[48:63]
	ds_read_b64_tr_b16 v[222:223], v184 offset:9216
	ds_read_b64_tr_b16 v[224:225], v184 offset:11264
	v_sub_f32_e32 v250, v249, v208
	v_cmp_ge_f32_e32 vcc, s40, v250
	v_max_f32_e32 v249, v208, v249
	v_sub_f32_e32 v250, v208, v249
	v_mul_f32_e32 v250, 0x3dd53b94, v250
	s_waitcnt lgkmcnt(6)
	v_mfma_f32_32x32x16_bf16 v[48:63], v[156:159], v[226:229], v[48:63]
	ds_read_b64_tr_b16 v[226:227], v184 offset:13312
	ds_read_b64_tr_b16 v[228:229], v184 offset:15360
	v_exp_f32_e32 v250, v250
	s_cmp_eq_u64 vcc, exec
	s_cselect_b64 s[10:11], -1, 0
	v_cndmask_b32_e64 v207, v250, 1.0, s[10:11]
	v_cndmask_b32_e64 v208, v249, v208, s[10:11]
	s_waitcnt lgkmcnt(6)
	v_mfma_f32_32x32x16_bf16 v[32:47], v[144:147], v[214:217], v[32:47]
	ds_read_b64_tr_b16 v[214:215], v184 offset:1536
	ds_read_b64_tr_b16 v[216:217], v184 offset:3584
	v_mul_f32_e32 v252, 0xbdd53b94, v208
	v_pk_fma_f32 v[80:81], v[80:81], s[96:97], v[252:253] op_sel_hi:[1,0,0]
	v_pk_fma_f32 v[82:83], v[82:83], s[96:97], v[252:253] op_sel_hi:[1,0,0]
	v_pk_fma_f32 v[84:85], v[84:85], s[96:97], v[252:253] op_sel_hi:[1,0,0]
	v_pk_fma_f32 v[86:87], v[86:87], s[96:97], v[252:253] op_sel_hi:[1,0,0]
	s_waitcnt lgkmcnt(6)
	v_mfma_f32_32x32x16_bf16 v[32:47], v[148:151], v[218:221], v[32:47]
	ds_read_b64_tr_b16 v[218:219], v184 offset:5632
	ds_read_b64_tr_b16 v[220:221], v184 offset:7680
	v_pk_fma_f32 v[88:89], v[88:89], s[96:97], v[252:253] op_sel_hi:[1,0,0]
	v_pk_fma_f32 v[90:91], v[90:91], s[96:97], v[252:253] op_sel_hi:[1,0,0]
	v_pk_fma_f32 v[92:93], v[92:93], s[96:97], v[252:253] op_sel_hi:[1,0,0]
	v_pk_fma_f32 v[94:95], v[94:95], s[96:97], v[252:253] op_sel_hi:[1,0,0]
	v_exp_f32_e32 v80, v80
	s_waitcnt lgkmcnt(6)
	v_mfma_f32_32x32x16_bf16 v[32:47], v[152:155], v[222:225], v[32:47]
	ds_read_b64_tr_b16 v[222:223], v184 offset:9728
	ds_read_b64_tr_b16 v[224:225], v184 offset:11776
	v_pk_fma_f32 v[64:65], v[64:65], s[96:97], v[252:253] op_sel_hi:[1,0,0]
	v_exp_f32_e32 v81, v81
	v_exp_f32_e32 v82, v82
	v_pk_fma_f32 v[66:67], v[66:67], s[96:97], v[252:253] op_sel_hi:[1,0,0]
	v_exp_f32_e32 v83, v83
	s_waitcnt lgkmcnt(6)
	v_mfma_f32_32x32x16_bf16 v[32:47], v[156:159], v[226:229], v[32:47]
	ds_read_b64_tr_b16 v[226:227], v184 offset:13824
	ds_read_b64_tr_b16 v[228:229], v184 offset:15872
	v_exp_f32_e32 v84, v84
	v_pk_fma_f32 v[68:69], v[68:69], s[96:97], v[252:253] op_sel_hi:[1,0,0]
	v_exp_f32_e32 v85, v85
	v_pk_add_f32 v[212:213], v[80:81], v[82:83]
	v_exp_f32_e32 v86, v86
	s_waitcnt lgkmcnt(6)
	v_mfma_f32_32x32x16_bf16 v[16:31], v[144:147], v[214:217], v[16:31]
	v_pk_fma_f32 v[70:71], v[70:71], s[96:97], v[252:253] op_sel_hi:[1,0,0]
	v_exp_f32_e32 v87, v87
	v_pk_add_f32 v[212:213], v[212:213], v[84:85]
	v_exp_f32_e32 v88, v88
	v_pk_fma_f32 v[72:73], v[72:73], s[96:97], v[252:253] op_sel_hi:[1,0,0]
	s_waitcnt lgkmcnt(4)
	v_mfma_f32_32x32x16_bf16 v[16:31], v[148:151], v[218:221], v[16:31]
	v_exp_f32_e32 v89, v89
	v_pk_add_f32 v[212:213], v[212:213], v[86:87]
	v_exp_f32_e32 v90, v90
	v_pk_fma_f32 v[74:75], v[74:75], s[96:97], v[252:253] op_sel_hi:[1,0,0]
	v_exp_f32_e32 v91, v91
	s_waitcnt lgkmcnt(2)
	v_mfma_f32_32x32x16_bf16 v[16:31], v[152:155], v[222:225], v[16:31]
	v_pk_add_f32 v[212:213], v[212:213], v[88:89]
	v_exp_f32_e32 v92, v92
	v_pk_fma_f32 v[76:77], v[76:77], s[96:97], v[252:253] op_sel_hi:[1,0,0]
	v_exp_f32_e32 v93, v93
	v_pk_add_f32 v[212:213], v[212:213], v[90:91]
	s_waitcnt lgkmcnt(0)
	v_mfma_f32_32x32x16_bf16 v[16:31], v[156:159], v[226:229], v[16:31]
	v_exp_f32_e32 v94, v94
	v_pk_fma_f32 v[78:79], v[78:79], s[96:97], v[252:253] op_sel_hi:[1,0,0]
	v_exp_f32_e32 v95, v95
	v_pk_add_f32 v[212:213], v[212:213], v[92:93]
	v_pk_add_f32 v[212:213], v[212:213], v[94:95]
	v_cvt_pk_bf16_f32 v144, v80, v81
	v_cvt_pk_bf16_f32 v145, v82, v83
	v_cvt_pk_bf16_f32 v146, v84, v85
	v_cvt_pk_bf16_f32 v147, v86, v87
	v_cvt_pk_bf16_f32 v148, v88, v89
	v_cvt_pk_bf16_f32 v149, v90, v91
	v_cvt_pk_bf16_f32 v150, v92, v93
	v_cvt_pk_bf16_f32 v151, v94, v95
	v_permlane32_swap_b32_e32 v144, v146
	v_permlane32_swap_b32_e32 v145, v147
	v_permlane32_swap_b32_e32 v148, v150
	v_permlane32_swap_b32_e32 v149, v151
	v_cmp_gt_f32_e32 vcc, 1.0, v207
	s_cbranch_vccz .Lmla_noresc_e
	s_and_saveexec_b64 s[0:1], s[8:9]
	ds_write_b32 v182, v207 offset:128
	s_or_b64 exec, exec, s[0:1]
	s_waitcnt lgkmcnt(0)
	v_add_u32_e32 v253, s50, v181
	ds_read_b128 v[92:95], v253 offset:224
	ds_read_b128 v[88:91], v253 offset:192
	ds_read_b128 v[84:87], v253 offset:160
	ds_read_b128 v[80:83], v253 offset:128
	s_waitcnt lgkmcnt(3)
	v_pk_mul_f32 v[12:13], v[12:13], v[92:93]
	v_pk_mul_f32 v[14:15], v[14:15], v[94:95]
	v_pk_mul_f32 v[60:61], v[60:61], v[92:93]
	v_pk_mul_f32 v[62:63], v[62:63], v[94:95]
	v_pk_mul_f32 v[44:45], v[44:45], v[92:93]
	v_pk_mul_f32 v[46:47], v[46:47], v[94:95]
	v_pk_mul_f32 v[28:29], v[28:29], v[92:93]
	v_pk_mul_f32 v[30:31], v[30:31], v[94:95]
	s_waitcnt lgkmcnt(2)
	v_pk_mul_f32 v[8:9], v[8:9], v[88:89]
	v_pk_mul_f32 v[10:11], v[10:11], v[90:91]
	v_pk_mul_f32 v[56:57], v[56:57], v[88:89]
	v_pk_mul_f32 v[58:59], v[58:59], v[90:91]
	v_pk_mul_f32 v[40:41], v[40:41], v[88:89]
	v_pk_mul_f32 v[42:43], v[42:43], v[90:91]
	v_pk_mul_f32 v[24:25], v[24:25], v[88:89]
	v_pk_mul_f32 v[26:27], v[26:27], v[90:91]
	s_waitcnt lgkmcnt(1)
	v_pk_mul_f32 v[4:5], v[4:5], v[84:85]
	v_pk_mul_f32 v[6:7], v[6:7], v[86:87]
	v_pk_mul_f32 v[52:53], v[52:53], v[84:85]
	v_pk_mul_f32 v[54:55], v[54:55], v[86:87]
	v_pk_mul_f32 v[36:37], v[36:37], v[84:85]
	v_pk_mul_f32 v[38:39], v[38:39], v[86:87]
	v_pk_mul_f32 v[20:21], v[20:21], v[84:85]
	v_pk_mul_f32 v[22:23], v[22:23], v[86:87]
	s_waitcnt lgkmcnt(0)
	v_pk_mul_f32 v[0:1], v[0:1], v[80:81]
	v_pk_mul_f32 v[2:3], v[2:3], v[82:83]
	v_pk_mul_f32 v[48:49], v[48:49], v[80:81]
	v_pk_mul_f32 v[50:51], v[50:51], v[82:83]
	v_pk_mul_f32 v[32:33], v[32:33], v[80:81]
	v_pk_mul_f32 v[34:35], v[34:35], v[82:83]
	v_pk_mul_f32 v[16:17], v[16:17], v[80:81]
	v_pk_mul_f32 v[18:19], v[18:19], v[82:83]
.Lmla_noresc_e:
	s_add_i32 s58, s58, 1
	s_addk_i32 s51, 0x80
	s_waitcnt vmcnt(0) lgkmcnt(0)
	s_barrier
	s_cmp_ge_u32 s58, s19
	s_cbranch_scc0 .Lmla_loop
	ds_read_b128 v[230:233], v193 offset:57344
	ds_read_b128 v[234:237], v186 offset:57344
	ds_read_b128 v[238:241], v187 offset:57344
	ds_read_b128 v[242:245], v188 offset:57344
	s_mov_b32 m0, s54
	v_lshl_add_u64 v[254:255], v[164:165], 1, s[100:101]
	global_load_lds_dwordx4 v[254:255], off
	s_mov_b32 m0, s55
	v_lshl_add_u64 v[254:255], v[166:167], 1, s[100:101]
	global_load_lds_dwordx4 v[254:255], off
	v_exp_f32_e32 v64, v64
	v_exp_f32_e32 v65, v65
	v_exp_f32_e32 v66, v66
	v_exp_f32_e32 v67, v67
	v_pk_add_f32 v[212:213], v[212:213], v[64:65]
	v_exp_f32_e32 v68, v68
	s_waitcnt lgkmcnt(3)
	v_mfma_f32_32x32x16_bf16 v[80:95], v[230:233], v[124:127], 0
	ds_read_b128 v[230:233], v189 offset:57344
	v_exp_f32_e32 v69, v69
	v_pk_add_f32 v[212:213], v[212:213], v[66:67]
	v_exp_f32_e32 v70, v70
	s_waitcnt lgkmcnt(3)
	v_mfma_f32_32x32x16_bf16 v[80:95], v[234:237], v[120:123], v[80:95]
	ds_read_b128 v[234:237], v190 offset:57344
	v_exp_f32_e32 v71, v71
	v_pk_add_f32 v[212:213], v[212:213], v[68:69]
	v_exp_f32_e32 v72, v72
	s_waitcnt lgkmcnt(3)
	v_mfma_f32_32x32x16_bf16 v[80:95], v[238:241], v[116:119], v[80:95]
	ds_read_b128 v[238:241], v191 offset:57344
	v_exp_f32_e32 v73, v73
	v_pk_add_f32 v[212:213], v[212:213], v[70:71]
	v_exp_f32_e32 v74, v74
	s_waitcnt lgkmcnt(3)
	v_mfma_f32_32x32x16_bf16 v[80:95], v[242:245], v[112:115], v[80:95]
	ds_read_b128 v[242:245], v192 offset:57344
	v_exp_f32_e32 v75, v75
	v_pk_add_f32 v[212:213], v[212:213], v[72:73]
	v_exp_f32_e32 v76, v76
	s_waitcnt lgkmcnt(3)
	v_mfma_f32_32x32x16_bf16 v[80:95], v[230:233], v[108:111], v[80:95]
	v_add_u32_e32 v211, 0x6000, v203
	ds_read_b128 v[230:233], v211 offset:49152
	v_exp_f32_e32 v77, v77
	v_pk_add_f32 v[212:213], v[212:213], v[74:75]
	v_exp_f32_e32 v78, v78
	s_waitcnt lgkmcnt(3)
	v_mfma_f32_32x32x16_bf16 v[80:95], v[234:237], v[104:107], v[80:95]
	v_add_u32_e32 v211, 0x6000, v204
	ds_read_b128 v[234:237], v211 offset:49152
	v_exp_f32_e32 v79, v79
	v_pk_add_f32 v[212:213], v[212:213], v[76:77]
	v_pk_add_f32 v[212:213], v[212:213], v[78:79]
	s_waitcnt lgkmcnt(3)
	v_mfma_f32_32x32x16_bf16 v[80:95], v[238:241], v[100:103], v[80:95]
	v_add_u32_e32 v211, 0x6000, v205
	ds_read_b128 v[238:241], v211 offset:49152
	v_add_f32_e32 v212, v212, v213
	v_mov_b32_e32 v213, v212
	v_cvt_pk_bf16_f32 v152, v64, v65
	s_waitcnt lgkmcnt(3)
	v_mfma_f32_32x32x16_bf16 v[80:95], v[242:245], v[96:99], v[80:95]
	v_add_u32_e32 v211, 0x6000, v206
	ds_read_b128 v[242:245], v211 offset:49152
	v_cvt_pk_bf16_f32 v153, v66, v67
	v_cvt_pk_bf16_f32 v154, v68, v69
	v_cvt_pk_bf16_f32 v155, v70, v71
	s_waitcnt lgkmcnt(3)
	v_mfma_f32_32x32x16_bf16 v[80:95], v[230:233], v[128:131], v[80:95]
	v_add_u32_e32 v211, v209, v194
	ds_read_b128 v[230:233], v211 offset:8192
	v_cvt_pk_bf16_f32 v156, v72, v73
	v_cvt_pk_bf16_f32 v157, v74, v75
	v_cvt_pk_bf16_f32 v158, v76, v77
	s_waitcnt lgkmcnt(3)
	v_mfma_f32_32x32x16_bf16 v[80:95], v[234:237], v[132:135], v[80:95]
	v_add_u32_e32 v211, v209, v195
	ds_read_b128 v[234:237], v211 offset:8192
	v_cvt_pk_bf16_f32 v159, v78, v79
	v_permlane32_swap_b32_e32 v212, v213
	v_add_f32_e32 v251, v212, v213
	s_waitcnt lgkmcnt(3)
	v_mfma_f32_32x32x16_bf16 v[80:95], v[238:241], v[136:139], v[80:95]
	v_add_u32_e32 v211, v209, v196
	ds_read_b128 v[238:241], v211 offset:8192
	v_fma_f32 v183, v207, v183, v251
	v_permlane32_swap_b32_e32 v152, v154
	v_permlane32_swap_b32_e32 v153, v155
	s_waitcnt lgkmcnt(3)
	v_mfma_f32_32x32x16_bf16 v[80:95], v[242:245], v[140:143], v[80:95]
	v_add_u32_e32 v211, v209, v197
	ds_read_b128 v[242:245], v211 offset:8192
	v_permlane32_swap_b32_e32 v156, v158
	v_permlane32_swap_b32_e32 v157, v159
	s_waitcnt lgkmcnt(3)
	v_mfma_f32_32x32x16_bf16 v[64:79], v[230:233], v[124:127], 0
	v_add_u32_e32 v211, v209, v198
	ds_read_b128 v[230:233], v211 offset:8192
	s_waitcnt lgkmcnt(3)
	v_mfma_f32_32x32x16_bf16 v[64:79], v[234:237], v[120:123], v[64:79]
	v_add_u32_e32 v211, v209, v199
	ds_read_b128 v[234:237], v211 offset:8192
	s_waitcnt lgkmcnt(3)
	v_mfma_f32_32x32x16_bf16 v[64:79], v[238:241], v[116:119], v[64:79]
	v_add_u32_e32 v211, v209, v200
	ds_read_b128 v[238:241], v211 offset:8192
	s_waitcnt lgkmcnt(3)
	v_mfma_f32_32x32x16_bf16 v[64:79], v[242:245], v[112:115], v[64:79]
	v_add_u32_e32 v211, v209, v201
	ds_read_b128 v[242:245], v211 offset:8192
	s_waitcnt lgkmcnt(3)
	v_mfma_f32_32x32x16_bf16 v[64:79], v[230:233], v[108:111], v[64:79]
	v_add_u32_e32 v211, 0x6000, v203
	ds_read_b128 v[230:233], v211 offset:53248
	s_waitcnt lgkmcnt(3)
	v_mfma_f32_32x32x16_bf16 v[64:79], v[234:237], v[104:107], v[64:79]
	v_add_u32_e32 v211, 0x6000, v204
	ds_read_b128 v[234:237], v211 offset:53248
	s_waitcnt lgkmcnt(3)
	v_mfma_f32_32x32x16_bf16 v[64:79], v[238:241], v[100:103], v[64:79]
	v_add_u32_e32 v211, 0x6000, v205
	ds_read_b128 v[238:241], v211 offset:53248
	v_max_f32_e32 v249, v80, v81
	v_max3_f32 v249, v249, v82, v83
	s_waitcnt lgkmcnt(3)
	v_mfma_f32_32x32x16_bf16 v[64:79], v[242:245], v[96:99], v[64:79]
	v_add_u32_e32 v211, 0x6000, v206
	ds_read_b128 v[242:245], v211 offset:53248
	v_max3_f32 v249, v249, v84, v85
	v_max3_f32 v249, v249, v86, v87
	s_waitcnt lgkmcnt(3)
	v_mfma_f32_32x32x16_bf16 v[64:79], v[230:233], v[128:131], v[64:79]
	ds_read_b64_tr_b16 v[214:215], v185
	ds_read_b64_tr_b16 v[216:217], v185 offset:2048
	v_max3_f32 v249, v249, v88, v89
	v_max3_f32 v249, v249, v90, v91
	s_waitcnt lgkmcnt(4)
	v_mfma_f32_32x32x16_bf16 v[64:79], v[234:237], v[132:135], v[64:79]
	ds_read_b64_tr_b16 v[218:219], v185 offset:4096
	ds_read_b64_tr_b16 v[220:221], v185 offset:6144
	v_max3_f32 v249, v249, v92, v93
	v_max3_f32 v249, v249, v94, v95
	s_waitcnt lgkmcnt(5)
	v_mfma_f32_32x32x16_bf16 v[64:79], v[238:241], v[136:139], v[64:79]
	ds_read_b64_tr_b16 v[222:223], v185 offset:8192
	ds_read_b64_tr_b16 v[224:225], v185 offset:10240
	s_waitcnt lgkmcnt(6)
	v_mfma_f32_32x32x16_bf16 v[64:79], v[242:245], v[140:143], v[64:79]
	ds_read_b64_tr_b16 v[226:227], v185 offset:12288
	ds_read_b64_tr_b16 v[228:229], v185 offset:14336
	s_waitcnt lgkmcnt(6)
	v_mfma_f32_32x32x16_bf16 v[0:15], v[144:147], v[214:217], v[0:15]
	ds_read_b64_tr_b16 v[214:215], v185 offset:512
	ds_read_b64_tr_b16 v[216:217], v185 offset:2560
	s_waitcnt lgkmcnt(6)
	v_mfma_f32_32x32x16_bf16 v[0:15], v[148:151], v[218:221], v[0:15]
	ds_read_b64_tr_b16 v[218:219], v185 offset:4608
	ds_read_b64_tr_b16 v[220:221], v185 offset:6656
	s_waitcnt lgkmcnt(6)
	v_mfma_f32_32x32x16_bf16 v[0:15], v[152:155], v[222:225], v[0:15]
	ds_read_b64_tr_b16 v[222:223], v185 offset:8704
	ds_read_b64_tr_b16 v[224:225], v185 offset:10752
	s_waitcnt lgkmcnt(6)
	v_mfma_f32_32x32x16_bf16 v[0:15], v[156:159], v[226:229], v[0:15]
	ds_read_b64_tr_b16 v[226:227], v185 offset:12800
	ds_read_b64_tr_b16 v[228:229], v185 offset:14848
	s_waitcnt lgkmcnt(6)
	v_mfma_f32_32x32x16_bf16 v[48:63], v[144:147], v[214:217], v[48:63]
	ds_read_b64_tr_b16 v[214:215], v185 offset:1024
	ds_read_b64_tr_b16 v[216:217], v185 offset:3072
	v_max3_f32 v249, v249, v64, v65
	v_max3_f32 v249, v249, v66, v67
	v_max3_f32 v249, v249, v68, v69
	v_max3_f32 v249, v249, v70, v71
	v_max3_f32 v249, v249, v72, v73
	v_max3_f32 v249, v249, v74, v75
	s_waitcnt lgkmcnt(6)
	v_mfma_f32_32x32x16_bf16 v[48:63], v[148:151], v[218:221], v[48:63]
	ds_read_b64_tr_b16 v[218:219], v185 offset:5120
	ds_read_b64_tr_b16 v[220:221], v185 offset:7168
	v_max3_f32 v249, v249, v76, v77
	v_max3_f32 v249, v249, v78, v79
	v_mov_b32_e32 v250, v249
	s_nop 1
	v_permlane32_swap_b32_e32 v249, v250
	v_max_f32_e32 v249, v249, v250
	s_waitcnt lgkmcnt(6)
	v_mfma_f32_32x32x16_bf16 v[48:63], v[152:155], v[222:225], v[48:63]
	ds_read_b64_tr_b16 v[222:223], v185 offset:9216
	ds_read_b64_tr_b16 v[224:225], v185 offset:11264
	v_sub_f32_e32 v250, v249, v208
	v_cmp_ge_f32_e32 vcc, s40, v250
	v_max_f32_e32 v249, v208, v249
	v_sub_f32_e32 v250, v208, v249
	v_mul_f32_e32 v250, 0x3dd53b94, v250
	s_waitcnt lgkmcnt(6)
	v_mfma_f32_32x32x16_bf16 v[48:63], v[156:159], v[226:229], v[48:63]
	ds_read_b64_tr_b16 v[226:227], v185 offset:13312
	ds_read_b64_tr_b16 v[228:229], v185 offset:15360
	v_exp_f32_e32 v250, v250
	s_cmp_eq_u64 vcc, exec
	s_cselect_b64 s[10:11], -1, 0
	v_cndmask_b32_e64 v207, v250, 1.0, s[10:11]
	v_cndmask_b32_e64 v208, v249, v208, s[10:11]
	s_waitcnt lgkmcnt(6)
	v_mfma_f32_32x32x16_bf16 v[32:47], v[144:147], v[214:217], v[32:47]
	ds_read_b64_tr_b16 v[214:215], v185 offset:1536
	ds_read_b64_tr_b16 v[216:217], v185 offset:3584
	v_mul_f32_e32 v252, 0xbdd53b94, v208
	v_pk_fma_f32 v[80:81], v[80:81], s[96:97], v[252:253] op_sel_hi:[1,0,0]
	v_pk_fma_f32 v[82:83], v[82:83], s[96:97], v[252:253] op_sel_hi:[1,0,0]
	v_pk_fma_f32 v[84:85], v[84:85], s[96:97], v[252:253] op_sel_hi:[1,0,0]
	v_pk_fma_f32 v[86:87], v[86:87], s[96:97], v[252:253] op_sel_hi:[1,0,0]
	s_waitcnt lgkmcnt(6)
	v_mfma_f32_32x32x16_bf16 v[32:47], v[148:151], v[218:221], v[32:47]
	ds_read_b64_tr_b16 v[218:219], v185 offset:5632
	ds_read_b64_tr_b16 v[220:221], v185 offset:7680
	v_pk_fma_f32 v[88:89], v[88:89], s[96:97], v[252:253] op_sel_hi:[1,0,0]
	v_pk_fma_f32 v[90:91], v[90:91], s[96:97], v[252:253] op_sel_hi:[1,0,0]
	v_pk_fma_f32 v[92:93], v[92:93], s[96:97], v[252:253] op_sel_hi:[1,0,0]
	v_pk_fma_f32 v[94:95], v[94:95], s[96:97], v[252:253] op_sel_hi:[1,0,0]
	v_exp_f32_e32 v80, v80
	s_waitcnt lgkmcnt(6)
	v_mfma_f32_32x32x16_bf16 v[32:47], v[152:155], v[222:225], v[32:47]
	ds_read_b64_tr_b16 v[222:223], v185 offset:9728
	ds_read_b64_tr_b16 v[224:225], v185 offset:11776
	v_pk_fma_f32 v[64:65], v[64:65], s[96:97], v[252:253] op_sel_hi:[1,0,0]
	v_exp_f32_e32 v81, v81
	v_exp_f32_e32 v82, v82
	v_pk_fma_f32 v[66:67], v[66:67], s[96:97], v[252:253] op_sel_hi:[1,0,0]
	v_exp_f32_e32 v83, v83
	s_waitcnt lgkmcnt(6)
	v_mfma_f32_32x32x16_bf16 v[32:47], v[156:159], v[226:229], v[32:47]
	ds_read_b64_tr_b16 v[226:227], v185 offset:13824
	ds_read_b64_tr_b16 v[228:229], v185 offset:15872
	v_exp_f32_e32 v84, v84
	v_pk_fma_f32 v[68:69], v[68:69], s[96:97], v[252:253] op_sel_hi:[1,0,0]
	v_exp_f32_e32 v85, v85
	v_pk_add_f32 v[212:213], v[80:81], v[82:83]
	v_exp_f32_e32 v86, v86
	s_waitcnt lgkmcnt(6)
	v_mfma_f32_32x32x16_bf16 v[16:31], v[144:147], v[214:217], v[16:31]
	v_pk_fma_f32 v[70:71], v[70:71], s[96:97], v[252:253] op_sel_hi:[1,0,0]
	v_exp_f32_e32 v87, v87
	v_pk_add_f32 v[212:213], v[212:213], v[84:85]
	v_exp_f32_e32 v88, v88
	v_pk_fma_f32 v[72:73], v[72:73], s[96:97], v[252:253] op_sel_hi:[1,0,0]
	s_waitcnt lgkmcnt(4)
	v_mfma_f32_32x32x16_bf16 v[16:31], v[148:151], v[218:221], v[16:31]
	v_exp_f32_e32 v89, v89
	v_pk_add_f32 v[212:213], v[212:213], v[86:87]
	v_exp_f32_e32 v90, v90
	v_pk_fma_f32 v[74:75], v[74:75], s[96:97], v[252:253] op_sel_hi:[1,0,0]
	v_exp_f32_e32 v91, v91
	s_waitcnt lgkmcnt(2)
	v_mfma_f32_32x32x16_bf16 v[16:31], v[152:155], v[222:225], v[16:31]
	v_pk_add_f32 v[212:213], v[212:213], v[88:89]
	v_exp_f32_e32 v92, v92
	v_pk_fma_f32 v[76:77], v[76:77], s[96:97], v[252:253] op_sel_hi:[1,0,0]
	v_exp_f32_e32 v93, v93
	v_pk_add_f32 v[212:213], v[212:213], v[90:91]
	s_waitcnt lgkmcnt(0)
	v_mfma_f32_32x32x16_bf16 v[16:31], v[156:159], v[226:229], v[16:31]
	v_exp_f32_e32 v94, v94
	v_pk_fma_f32 v[78:79], v[78:79], s[96:97], v[252:253] op_sel_hi:[1,0,0]
	v_exp_f32_e32 v95, v95
	v_pk_add_f32 v[212:213], v[212:213], v[92:93]
	v_pk_add_f32 v[212:213], v[212:213], v[94:95]
	v_cvt_pk_bf16_f32 v144, v80, v81
	v_cvt_pk_bf16_f32 v145, v82, v83
	v_cvt_pk_bf16_f32 v146, v84, v85
	v_cvt_pk_bf16_f32 v147, v86, v87
	v_cvt_pk_bf16_f32 v148, v88, v89
	v_cvt_pk_bf16_f32 v149, v90, v91
	v_cvt_pk_bf16_f32 v150, v92, v93
	v_cvt_pk_bf16_f32 v151, v94, v95
	v_permlane32_swap_b32_e32 v144, v146
	v_permlane32_swap_b32_e32 v145, v147
	v_permlane32_swap_b32_e32 v148, v150
	v_permlane32_swap_b32_e32 v149, v151
	v_cmp_gt_f32_e32 vcc, 1.0, v207
	s_cbranch_vccz .Lmla_noresc_t
	s_and_saveexec_b64 s[0:1], s[8:9]
	ds_write_b32 v182, v207 offset:128
	s_or_b64 exec, exec, s[0:1]
	s_waitcnt lgkmcnt(0)
	v_add_u32_e32 v253, s50, v181
	ds_read_b128 v[92:95], v253 offset:224
	ds_read_b128 v[88:91], v253 offset:192
	ds_read_b128 v[84:87], v253 offset:160
	ds_read_b128 v[80:83], v253 offset:128
	s_waitcnt lgkmcnt(3)
	v_pk_mul_f32 v[12:13], v[12:13], v[92:93]
	v_pk_mul_f32 v[14:15], v[14:15], v[94:95]
	v_pk_mul_f32 v[60:61], v[60:61], v[92:93]
	v_pk_mul_f32 v[62:63], v[62:63], v[94:95]
	v_pk_mul_f32 v[44:45], v[44:45], v[92:93]
	v_pk_mul_f32 v[46:47], v[46:47], v[94:95]
	v_pk_mul_f32 v[28:29], v[28:29], v[92:93]
	v_pk_mul_f32 v[30:31], v[30:31], v[94:95]
	s_waitcnt lgkmcnt(2)
	v_pk_mul_f32 v[8:9], v[8:9], v[88:89]
	v_pk_mul_f32 v[10:11], v[10:11], v[90:91]
	v_pk_mul_f32 v[56:57], v[56:57], v[88:89]
	v_pk_mul_f32 v[58:59], v[58:59], v[90:91]
	v_pk_mul_f32 v[40:41], v[40:41], v[88:89]
	v_pk_mul_f32 v[42:43], v[42:43], v[90:91]
	v_pk_mul_f32 v[24:25], v[24:25], v[88:89]
	v_pk_mul_f32 v[26:27], v[26:27], v[90:91]
	s_waitcnt lgkmcnt(1)
	v_pk_mul_f32 v[4:5], v[4:5], v[84:85]
	v_pk_mul_f32 v[6:7], v[6:7], v[86:87]
	v_pk_mul_f32 v[52:53], v[52:53], v[84:85]
	v_pk_mul_f32 v[54:55], v[54:55], v[86:87]
	v_pk_mul_f32 v[36:37], v[36:37], v[84:85]
	v_pk_mul_f32 v[38:39], v[38:39], v[86:87]
	v_pk_mul_f32 v[20:21], v[20:21], v[84:85]
	v_pk_mul_f32 v[22:23], v[22:23], v[86:87]
	s_waitcnt lgkmcnt(0)
	v_pk_mul_f32 v[0:1], v[0:1], v[80:81]
	v_pk_mul_f32 v[2:3], v[2:3], v[82:83]
	v_pk_mul_f32 v[48:49], v[48:49], v[80:81]
	v_pk_mul_f32 v[50:51], v[50:51], v[82:83]
	v_pk_mul_f32 v[32:33], v[32:33], v[80:81]
	v_pk_mul_f32 v[34:35], v[34:35], v[82:83]
	v_pk_mul_f32 v[16:17], v[16:17], v[80:81]
	v_pk_mul_f32 v[18:19], v[18:19], v[82:83]
.Lmla_noresc_t:
	s_waitcnt vmcnt(0) lgkmcnt(0)
	s_barrier
	ds_read_b64_tr_b16 v[214:215], v184
	ds_read_b64_tr_b16 v[216:217], v184 offset:2048
	ds_read_b64_tr_b16 v[218:219], v184 offset:4096
	ds_read_b64_tr_b16 v[220:221], v184 offset:6144
	ds_read_b64_tr_b16 v[222:223], v184 offset:8192
	ds_read_b64_tr_b16 v[224:225], v184 offset:10240
	ds_read_b64_tr_b16 v[226:227], v184 offset:12288
	ds_read_b64_tr_b16 v[228:229], v184 offset:14336
	v_exp_f32_e32 v64, v64
	v_exp_f32_e32 v65, v65
	v_exp_f32_e32 v66, v66
	v_exp_f32_e32 v67, v67
	v_pk_add_f32 v[212:213], v[212:213], v[64:65]
	v_exp_f32_e32 v68, v68
	v_exp_f32_e32 v69, v69
	v_pk_add_f32 v[212:213], v[212:213], v[66:67]
	v_exp_f32_e32 v70, v70
	v_exp_f32_e32 v71, v71
	v_pk_add_f32 v[212:213], v[212:213], v[68:69]
	v_exp_f32_e32 v72, v72
	v_exp_f32_e32 v73, v73
	v_pk_add_f32 v[212:213], v[212:213], v[70:71]
	v_exp_f32_e32 v74, v74
	v_exp_f32_e32 v75, v75
	v_pk_add_f32 v[212:213], v[212:213], v[72:73]
	v_exp_f32_e32 v76, v76
	v_exp_f32_e32 v77, v77
	v_pk_add_f32 v[212:213], v[212:213], v[74:75]
	v_exp_f32_e32 v78, v78
	v_exp_f32_e32 v79, v79
	v_pk_add_f32 v[212:213], v[212:213], v[76:77]
	v_pk_add_f32 v[212:213], v[212:213], v[78:79]
	v_add_f32_e32 v212, v212, v213
	v_mov_b32_e32 v213, v212
	v_cvt_pk_bf16_f32 v152, v64, v65
	v_cvt_pk_bf16_f32 v153, v66, v67
	v_cvt_pk_bf16_f32 v154, v68, v69
	v_cvt_pk_bf16_f32 v155, v70, v71
	v_cvt_pk_bf16_f32 v156, v72, v73
	v_cvt_pk_bf16_f32 v157, v74, v75
	v_cvt_pk_bf16_f32 v158, v76, v77
	v_cvt_pk_bf16_f32 v159, v78, v79
	v_permlane32_swap_b32_e32 v212, v213
	v_add_f32_e32 v251, v212, v213
	v_fma_f32 v183, v207, v183, v251
	v_permlane32_swap_b32_e32 v152, v154
	v_permlane32_swap_b32_e32 v153, v155
	v_permlane32_swap_b32_e32 v156, v158
	v_permlane32_swap_b32_e32 v157, v159
	s_waitcnt lgkmcnt(6)
	v_mfma_f32_32x32x16_bf16 v[0:15], v[144:147], v[214:217], v[0:15]
	ds_read_b64_tr_b16 v[214:215], v184 offset:512
	ds_read_b64_tr_b16 v[216:217], v184 offset:2560
	s_waitcnt lgkmcnt(6)
	v_mfma_f32_32x32x16_bf16 v[0:15], v[148:151], v[218:221], v[0:15]
	ds_read_b64_tr_b16 v[218:219], v184 offset:4608
	ds_read_b64_tr_b16 v[220:221], v184 offset:6656
	s_waitcnt lgkmcnt(6)
	v_mfma_f32_32x32x16_bf16 v[0:15], v[152:155], v[222:225], v[0:15]
	ds_read_b64_tr_b16 v[222:223], v184 offset:8704
	ds_read_b64_tr_b16 v[224:225], v184 offset:10752
	s_waitcnt lgkmcnt(6)
	v_mfma_f32_32x32x16_bf16 v[0:15], v[156:159], v[226:229], v[0:15]
	ds_read_b64_tr_b16 v[226:227], v184 offset:12800
	ds_read_b64_tr_b16 v[228:229], v184 offset:14848
	s_waitcnt lgkmcnt(6)
	v_mfma_f32_32x32x16_bf16 v[48:63], v[144:147], v[214:217], v[48:63]
	ds_read_b64_tr_b16 v[214:215], v184 offset:1024
	ds_read_b64_tr_b16 v[216:217], v184 offset:3072
	s_waitcnt lgkmcnt(6)
	v_mfma_f32_32x32x16_bf16 v[48:63], v[148:151], v[218:221], v[48:63]
	ds_read_b64_tr_b16 v[218:219], v184 offset:5120
	ds_read_b64_tr_b16 v[220:221], v184 offset:7168
	s_waitcnt lgkmcnt(6)
	v_mfma_f32_32x32x16_bf16 v[48:63], v[152:155], v[222:225], v[48:63]
	ds_read_b64_tr_b16 v[222:223], v184 offset:9216
	ds_read_b64_tr_b16 v[224:225], v184 offset:11264
	s_waitcnt lgkmcnt(6)
	v_mfma_f32_32x32x16_bf16 v[48:63], v[156:159], v[226:229], v[48:63]
	ds_read_b64_tr_b16 v[226:227], v184 offset:13312
	ds_read_b64_tr_b16 v[228:229], v184 offset:15360
	s_waitcnt lgkmcnt(6)
	v_mfma_f32_32x32x16_bf16 v[32:47], v[144:147], v[214:217], v[32:47]
	ds_read_b64_tr_b16 v[214:215], v184 offset:1536
	ds_read_b64_tr_b16 v[216:217], v184 offset:3584
	s_waitcnt lgkmcnt(6)
	v_mfma_f32_32x32x16_bf16 v[32:47], v[148:151], v[218:221], v[32:47]
	ds_read_b64_tr_b16 v[218:219], v184 offset:5632
	ds_read_b64_tr_b16 v[220:221], v184 offset:7680
	s_waitcnt lgkmcnt(6)
	v_mfma_f32_32x32x16_bf16 v[32:47], v[152:155], v[222:225], v[32:47]
	ds_read_b64_tr_b16 v[222:223], v184 offset:9728
	ds_read_b64_tr_b16 v[224:225], v184 offset:11776
	s_waitcnt lgkmcnt(6)
	v_mfma_f32_32x32x16_bf16 v[32:47], v[156:159], v[226:229], v[32:47]
	ds_read_b64_tr_b16 v[226:227], v184 offset:13824
	ds_read_b64_tr_b16 v[228:229], v184 offset:15872
	s_waitcnt lgkmcnt(6)
	v_mfma_f32_32x32x16_bf16 v[16:31], v[144:147], v[214:217], v[16:31]
	s_waitcnt lgkmcnt(4)
	v_mfma_f32_32x32x16_bf16 v[16:31], v[148:151], v[218:221], v[16:31]
	s_waitcnt lgkmcnt(2)
	v_mfma_f32_32x32x16_bf16 v[16:31], v[152:155], v[222:225], v[16:31]
	s_waitcnt lgkmcnt(0)
	v_mfma_f32_32x32x16_bf16 v[16:31], v[156:159], v[226:229], v[16:31]
	s_and_saveexec_b64 s[0:1], s[8:9]
	s_cbranch_execz .LBB0_550
	ds_write_b32 v182, v183
	s_branch .LBB0_550
